# MLA attention: six K-fragment LDS reads kept in flight ahead of the QK MFMA chain
# baseline (speedup 1.0000x reference)
; #define MFMA32(a, b, c) __builtin_amdgcn_mfma_f32_32x32x16_bf16((a), (b), (c), 0, 0, 0)
; template <int DK, int DV, bool BIAS>
; DI void attn_item(u16* lds, const u16* __restrict__ Q, const u16* __restrict__ Kg, const u16* __restrict__ VT,
;                   const float* __restrict__ cum, u16* __restrict__ O, int ldo, int bh, int qb, int wid_k) {
;     ...
;     const u16* ldsK = lds + (kt & 1) * TILE_U16_; const u16* ldsV = ldsK + 64 * KSTR; const float* ldsC = (const float*)(ldsV + DV * 72);
; #pragma unroll
;     for (int kh = 0; kh < 2; ++kh) {
;       const int kb = k0 + kh * 32;
;       if (kb > wq0 + 31) continue;
;       f32x16 st;
; #pragma unroll
;       for (int i = 0; i < 16; ++i) st[i] = 0.f;
; #pragma unroll
;       for (int ks = 0; ks < NKS; ++ks) {
;         const bf16x8 kf = *(const bf16x8*)(ldsK + (kh * 32 + l31) * KSTR + ks * 16 + h2 * 8);
;         st = MFMA32(kf, qf[ks], st);
;       }
;       if (BIAS) {
; #pragma unroll
;         for (int g = 0; g < 4; ++g) {
;           const float4 ck = *(const float4*)(ldsC + kh * 32 + 8 * g + 4 * h2);
;           st[4 * g + 0] += cq - ck.x; st[4 * g + 1] += cq - ck.y; st[4 * g + 2] += cq - ck.z; st[4 * g + 3] += cq - ck.w;
;         }
;       }
;       if (kb + 31 > wq0) {
; #pragma unroll
;         for (int i = 0; i < 16; ++i) {
;           const int key = kb + (i & 3) + 8 * (i >> 2) + 4 * h2;
;           if (key > qrow) st[i] = -1e30f;
;         }
;       }
.LBB0_1361:
	s_or_b64 exec, exec, s[40:41]
	s_bitcmp1_b32 s60, 0
	s_cselect_b32 s40, 0xad00, 0
	s_add_i32 s40, s40, 0
	v_lshl_add_u32 v0, v165, 1, s40
	v_add_u32_e32 v6, s40, v165
	v_cmp_le_i32_e32 vcc, s72, v202
	v_add_u32_e32 v7, v0, v203
	s_and_saveexec_b64 s[40:41], vcc
	s_cbranch_execz .LBB0_1367
	ds_read_b128 v[232:235], v7
	ds_read_b128 v[236:239], v7 offset:32
	ds_read_b128 v[240:243], v7 offset:64
	ds_read_b128 v[244:247], v7 offset:96
	ds_read_b128 v[248:251], v7 offset:128
	ds_read_b128 v[208:211], v7 offset:160
	s_add_i32 s48, s72, 31
	v_cmp_gt_i32_e32 vcc, s48, v193
	s_waitcnt lgkmcnt(5)
	v_mfma_f32_32x32x16_bf16 v[80:95], v[232:235], v[96:99], 0
	ds_read_b128 v[232:235], v7 offset:192
	s_waitcnt lgkmcnt(5)
	v_mfma_f32_32x32x16_bf16 v[80:95], v[236:239], v[100:103], v[80:95]
	ds_read_b128 v[236:239], v7 offset:224
	s_waitcnt lgkmcnt(5)
	v_mfma_f32_32x32x16_bf16 v[80:95], v[240:243], v[104:107], v[80:95]
	ds_read_b128 v[240:243], v7 offset:256
	s_waitcnt lgkmcnt(5)
	v_mfma_f32_32x32x16_bf16 v[80:95], v[244:247], v[108:111], v[80:95]
	ds_read_b128 v[244:247], v7 offset:288
	s_waitcnt lgkmcnt(5)
	v_mfma_f32_32x32x16_bf16 v[80:95], v[248:251], v[112:115], v[80:95]
	ds_read_b128 v[248:251], v7 offset:320
	s_waitcnt lgkmcnt(5)
	v_mfma_f32_32x32x16_bf16 v[80:95], v[208:211], v[116:119], v[80:95]
	ds_read_b128 v[208:211], v7 offset:352
	s_waitcnt lgkmcnt(5)
	v_mfma_f32_32x32x16_bf16 v[80:95], v[232:235], v[120:123], v[80:95]
	s_waitcnt lgkmcnt(4)
	v_mfma_f32_32x32x16_bf16 v[80:95], v[236:239], v[124:127], v[80:95]
	s_waitcnt lgkmcnt(3)
	v_mfma_f32_32x32x16_bf16 v[80:95], v[240:243], v[128:131], v[80:95]
	s_waitcnt lgkmcnt(2)
	v_mfma_f32_32x32x16_bf16 v[80:95], v[244:247], v[132:135], v[80:95]
	s_waitcnt lgkmcnt(1)
	v_mfma_f32_32x32x16_bf16 v[80:95], v[248:251], v[136:139], v[80:95]
	s_waitcnt lgkmcnt(0)
	v_mfma_f32_32x32x16_bf16 v[80:95], v[208:211], v[140:143], v[80:95]
	s_and_saveexec_b64 s[48:49], vcc
	s_cbranch_execz .LBB0_1364
	v_add_u32_e32 v0, s72, v196
	v_cmp_lt_i32_e32 vcc, v0, v166
	v_add_u32_e32 v2, 2, v0
	s_nop 6
	v_cndmask_b32_e32 v81, v229, v81, vcc
	v_cmp_le_i32_e32 vcc, v0, v166
	s_nop 1
	v_cndmask_b32_e32 v80, v229, v80, vcc
	v_cmp_le_i32_e32 vcc, v2, v166
	v_add_u32_e32 v2, 3, v0
	s_nop 0
	v_cndmask_b32_e32 v82, v229, v82, vcc
	v_cmp_le_i32_e32 vcc, v2, v166
	v_add_u32_e32 v2, 8, v0
	s_nop 0
	v_cndmask_b32_e32 v83, v229, v83, vcc
	v_cmp_le_i32_e32 vcc, v2, v166
	v_add_u32_e32 v2, 9, v0
	s_nop 0
	v_cndmask_b32_e32 v84, v229, v84, vcc
	v_cmp_le_i32_e32 vcc, v2, v166
	v_add_u32_e32 v2, 10, v0
	s_nop 0
	v_cndmask_b32_e32 v85, v229, v85, vcc
	v_cmp_le_i32_e32 vcc, v2, v166
	v_add_u32_e32 v2, 11, v0
	s_nop 0
	v_cndmask_b32_e32 v86, v229, v86, vcc
	v_cmp_le_i32_e32 vcc, v2, v166
	v_add_u32_e32 v2, 16, v0
	s_nop 0
	v_cndmask_b32_e32 v87, v229, v87, vcc
	v_cmp_le_i32_e32 vcc, v2, v166
	v_add_u32_e32 v2, 17, v0
	s_nop 0
	v_cndmask_b32_e32 v88, v229, v88, vcc
	v_cmp_le_i32_e32 vcc, v2, v166
	v_add_u32_e32 v2, 18, v0
	s_nop 0
	v_cndmask_b32_e32 v89, v229, v89, vcc
	v_cmp_le_i32_e32 vcc, v2, v166
	v_add_u32_e32 v2, 19, v0
	s_nop 0
	v_cndmask_b32_e32 v90, v229, v90, vcc
	v_cmp_le_i32_e32 vcc, v2, v166
	v_add_u32_e32 v2, 24, v0
	s_nop 0
	v_cndmask_b32_e32 v91, v229, v91, vcc
	v_cmp_le_i32_e32 vcc, v2, v166
	v_add_u32_e32 v2, 25, v0
	s_nop 0
	v_cndmask_b32_e32 v92, v229, v92, vcc
	v_cmp_le_i32_e32 vcc, v2, v166
	v_add_u32_e32 v2, 26, v0
	v_add_u32_e32 v0, 27, v0
	v_cndmask_b32_e32 v93, v229, v93, vcc
	v_cmp_le_i32_e32 vcc, v2, v166
	s_nop 1
	v_cndmask_b32_e32 v94, v229, v94, vcc
	v_cmp_le_i32_e32 vcc, v0, v166
	s_nop 1
	v_cndmask_b32_e32 v95, v229, v95, vcc

; #define MFMA32(a, b, c) __builtin_amdgcn_mfma_f32_32x32x16_bf16((a), (b), (c), 0, 0, 0)
; template <int DK, int DV, bool BIAS>
; DI void attn_item(u16* lds, const u16* __restrict__ Q, const u16* __restrict__ Kg, const u16* __restrict__ VT,
;                   const float* __restrict__ cum, u16* __restrict__ O, int ldo, int bh, int qb, int wid_k) {
;     ...
;     for (int kh = 0; kh < 2; ++kh) {
;       const int kb = k0 + kh * 32;
;       if (kb > wq0 + 31) continue;
;       f32x16 st;
; #pragma unroll
;       for (int i = 0; i < 16; ++i) st[i] = 0.f;
; #pragma unroll
;       for (int ks = 0; ks < NKS; ++ks) {
;         const bf16x8 kf = *(const bf16x8*)(ldsK + (kh * 32 + l31) * KSTR + ks * 16 + h2 * 8);
;         st = MFMA32(kf, qf[ks], st);
;       }
;       if (BIAS) {
; #pragma unroll
;         for (int g = 0; g < 4; ++g) {
;           const float4 ck = *(const float4*)(ldsC + kh * 32 + 8 * g + 4 * h2);
;           st[4 * g + 0] += cq - ck.x; st[4 * g + 1] += cq - ck.y; st[4 * g + 2] += cq - ck.z; st[4 * g + 3] += cq - ck.w;
;         }
;       }
;       if (kb + 31 > wq0) {
; #pragma unroll
;         for (int i = 0; i < 16; ++i) {
;           const int key = kb + (i & 3) + 8 * (i >> 2) + 4 * h2;
;           if (key > qrow) st[i] = -1e30f;
;         }
;       }
.LBB0_1367:
	s_or_b64 exec, exec, s[40:41]
	s_add_i32 s40, s72, 32
	v_cmp_le_i32_e32 vcc, s40, v202
	s_and_saveexec_b64 s[40:41], vcc
	s_cbranch_execz .LBB0_1356
	ds_read_b128 v[232:235], v7 offset:12800
	ds_read_b128 v[236:239], v7 offset:12832
	ds_read_b128 v[240:243], v7 offset:12864
	ds_read_b128 v[244:247], v7 offset:12896
	ds_read_b128 v[248:251], v7 offset:12928
	ds_read_b128 v[208:211], v7 offset:12960
	s_add_i32 s48, s72, 63
	v_cmp_gt_i32_e32 vcc, s48, v193
	s_waitcnt lgkmcnt(5)
	v_mfma_f32_32x32x16_bf16 v[80:95], v[232:235], v[96:99], 0
	ds_read_b128 v[232:235], v7 offset:12992
	s_waitcnt lgkmcnt(5)
	v_mfma_f32_32x32x16_bf16 v[80:95], v[236:239], v[100:103], v[80:95]
	ds_read_b128 v[236:239], v7 offset:13024
	s_waitcnt lgkmcnt(5)
	v_mfma_f32_32x32x16_bf16 v[80:95], v[240:243], v[104:107], v[80:95]
	ds_read_b128 v[240:243], v7 offset:13056
	s_waitcnt lgkmcnt(5)
	v_mfma_f32_32x32x16_bf16 v[80:95], v[244:247], v[108:111], v[80:95]
	ds_read_b128 v[244:247], v7 offset:13088
	s_waitcnt lgkmcnt(5)
	v_mfma_f32_32x32x16_bf16 v[80:95], v[248:251], v[112:115], v[80:95]
	ds_read_b128 v[248:251], v7 offset:13120
	s_waitcnt lgkmcnt(5)
	v_mfma_f32_32x32x16_bf16 v[80:95], v[208:211], v[116:119], v[80:95]
	ds_read_b128 v[208:211], v7 offset:13152
	s_waitcnt lgkmcnt(5)
	v_mfma_f32_32x32x16_bf16 v[80:95], v[232:235], v[120:123], v[80:95]
	s_waitcnt lgkmcnt(4)
	v_mfma_f32_32x32x16_bf16 v[80:95], v[236:239], v[124:127], v[80:95]
	s_waitcnt lgkmcnt(3)
	v_mfma_f32_32x32x16_bf16 v[80:95], v[240:243], v[128:131], v[80:95]
	s_waitcnt lgkmcnt(2)
	v_mfma_f32_32x32x16_bf16 v[80:95], v[244:247], v[132:135], v[80:95]
	s_waitcnt lgkmcnt(1)
	v_mfma_f32_32x32x16_bf16 v[80:95], v[248:251], v[136:139], v[80:95]
	s_waitcnt lgkmcnt(0)
	v_mfma_f32_32x32x16_bf16 v[80:95], v[208:211], v[140:143], v[80:95]
	s_and_saveexec_b64 s[48:49], vcc
	s_cbranch_execz .LBB0_1370
	v_add_u32_e32 v0, s72, v196
	v_add_u32_e32 v2, 32, v0
	v_cmp_lt_i32_e32 vcc, v2, v166
	s_nop 6
	v_cndmask_b32_e32 v81, v229, v81, vcc
	v_cmp_le_i32_e32 vcc, v2, v166
	v_add_u32_e32 v2, 34, v0
	s_nop 0
	v_cndmask_b32_e32 v80, v229, v80, vcc
	v_cmp_le_i32_e32 vcc, v2, v166
	v_add_u32_e32 v2, 35, v0
	s_nop 0
	v_cndmask_b32_e32 v82, v229, v82, vcc
	v_cmp_le_i32_e32 vcc, v2, v166
	v_add_u32_e32 v2, 40, v0
	s_nop 0
	v_cndmask_b32_e32 v83, v229, v83, vcc
	v_cmp_le_i32_e32 vcc, v2, v166
	v_add_u32_e32 v2, 41, v0
	s_nop 0
	v_cndmask_b32_e32 v84, v229, v84, vcc
	v_cmp_le_i32_e32 vcc, v2, v166
	v_add_u32_e32 v2, 42, v0
	s_nop 0
	v_cndmask_b32_e32 v85, v229, v85, vcc
	v_cmp_le_i32_e32 vcc, v2, v166
	v_add_u32_e32 v2, 43, v0
	s_nop 0
	v_cndmask_b32_e32 v86, v229, v86, vcc
	v_cmp_le_i32_e32 vcc, v2, v166
	v_add_u32_e32 v2, 48, v0
	s_nop 0
	v_cndmask_b32_e32 v87, v229, v87, vcc
	v_cmp_le_i32_e32 vcc, v2, v166
	v_add_u32_e32 v2, 49, v0
	s_nop 0
	v_cndmask_b32_e32 v88, v229, v88, vcc
	v_cmp_le_i32_e32 vcc, v2, v166
	v_add_u32_e32 v2, 50, v0
	s_nop 0
	v_cndmask_b32_e32 v89, v229, v89, vcc
	v_cmp_le_i32_e32 vcc, v2, v166
	v_add_u32_e32 v2, 51, v0
	s_nop 0
	v_cndmask_b32_e32 v90, v229, v90, vcc
	v_cmp_le_i32_e32 vcc, v2, v166
	v_add_u32_e32 v2, 56, v0
	s_nop 0
	v_cndmask_b32_e32 v91, v229, v91, vcc
	v_cmp_le_i32_e32 vcc, v2, v166
	v_add_u32_e32 v2, 57, v0
	s_nop 0
	v_cndmask_b32_e32 v92, v229, v92, vcc
	v_cmp_le_i32_e32 vcc, v2, v166
	v_add_u32_e32 v2, 58, v0
	v_add_u32_e32 v0, 59, v0
	v_cndmask_b32_e32 v93, v229, v93, vcc
	v_cmp_le_i32_e32 vcc, v2, v166
	s_nop 1
	v_cndmask_b32_e32 v94, v229, v94, vcc
	v_cmp_le_i32_e32 vcc, v0, v166
	s_nop 1
	v_cndmask_b32_e32 v95, v229, v95, vcc
